# w3 loop: ordering of v13 with a pre-wait so at most 15 LDS ops are outstanding
# baseline (speedup 1.0000x reference)
; __device__ __forceinline__ void filter_item(const Params& p, int l, int Lf, int t0, float* dst, float* hidT  , int wid0) {
;     ...
; #pragma unroll 16
;     for (int j = 0; j < 64; ++j) {
;         const float wa = w3[j * 1024 + tid], wb = w3[j * 1024 + 512 + tid];
; #pragma unroll
;         for (int g = 0; g < 8; ++g) { const f32x4 hv = *(const f32x4*)(hidT + j * 32 + 4 * g);
; #pragma unroll
;             for (int i = 0; i < 4; ++i) { acc0[4 * g + i] += hv[i] * wa; acc1[4 * g + i] += hv[i] * wb; } }
;     }
.Lw3_719_loop:
	s_waitcnt lgkmcnt(7)
	ds_read_b128 v[142:145], v186 offset:128
	ds_read_b128 v[146:149], v186 offset:144
	ds_read_b128 v[150:153], v186 offset:160
	ds_read_b128 v[154:157], v186 offset:176
	ds_read_b128 v[158:161], v186 offset:192
	ds_read_b128 v[162:165], v186 offset:208
	ds_read_b128 v[166:169], v186 offset:224
	ds_read_b128 v[170:173], v186 offset:240
	s_waitcnt vmcnt(2) lgkmcnt(8)
	v_pk_fma_f32 v[68:69], v[174:175], v[110:111], v[68:69] op_sel_hi:[0,1,1]
	v_pk_fma_f32 v[62:63], v[176:177], v[110:111], v[62:63] op_sel_hi:[0,1,1]
	v_pk_fma_f32 v[66:67], v[174:175], v[112:113], v[66:67] op_sel_hi:[0,1,1]
	v_pk_fma_f32 v[64:65], v[176:177], v[112:113], v[64:65] op_sel_hi:[0,1,1]
	v_pk_fma_f32 v[60:61], v[174:175], v[114:115], v[60:61] op_sel_hi:[0,1,1]
	v_pk_fma_f32 v[56:57], v[176:177], v[114:115], v[56:57] op_sel_hi:[0,1,1]
	v_pk_fma_f32 v[58:59], v[174:175], v[116:117], v[58:59] op_sel_hi:[0,1,1]
	v_pk_fma_f32 v[54:55], v[176:177], v[116:117], v[54:55] op_sel_hi:[0,1,1]
	v_pk_fma_f32 v[52:53], v[174:175], v[118:119], v[52:53] op_sel_hi:[0,1,1]
	v_pk_fma_f32 v[48:49], v[176:177], v[118:119], v[48:49] op_sel_hi:[0,1,1]
	v_pk_fma_f32 v[50:51], v[174:175], v[120:121], v[50:51] op_sel_hi:[0,1,1]
	v_pk_fma_f32 v[46:47], v[176:177], v[120:121], v[46:47] op_sel_hi:[0,1,1]
	v_pk_fma_f32 v[44:45], v[174:175], v[122:123], v[44:45] op_sel_hi:[0,1,1]
	v_pk_fma_f32 v[40:41], v[176:177], v[122:123], v[40:41] op_sel_hi:[0,1,1]
	v_pk_fma_f32 v[42:43], v[174:175], v[124:125], v[42:43] op_sel_hi:[0,1,1]
	v_pk_fma_f32 v[38:39], v[176:177], v[124:125], v[38:39] op_sel_hi:[0,1,1]
	v_pk_fma_f32 v[36:37], v[174:175], v[126:127], v[36:37] op_sel_hi:[0,1,1]
	v_pk_fma_f32 v[32:33], v[176:177], v[126:127], v[32:33] op_sel_hi:[0,1,1]
	v_pk_fma_f32 v[34:35], v[174:175], v[128:129], v[34:35] op_sel_hi:[0,1,1]
	v_pk_fma_f32 v[30:31], v[176:177], v[128:129], v[30:31] op_sel_hi:[0,1,1]
	v_pk_fma_f32 v[28:29], v[174:175], v[130:131], v[28:29] op_sel_hi:[0,1,1]
	v_pk_fma_f32 v[24:25], v[176:177], v[130:131], v[24:25] op_sel_hi:[0,1,1]
	v_pk_fma_f32 v[26:27], v[174:175], v[132:133], v[26:27] op_sel_hi:[0,1,1]
	v_pk_fma_f32 v[22:23], v[176:177], v[132:133], v[22:23] op_sel_hi:[0,1,1]
	v_pk_fma_f32 v[20:21], v[174:175], v[134:135], v[20:21] op_sel_hi:[0,1,1]
	v_pk_fma_f32 v[14:15], v[176:177], v[134:135], v[14:15] op_sel_hi:[0,1,1]
	v_pk_fma_f32 v[18:19], v[174:175], v[136:137], v[18:19] op_sel_hi:[0,1,1]
	v_pk_fma_f32 v[16:17], v[176:177], v[136:137], v[16:17] op_sel_hi:[0,1,1]
	v_pk_fma_f32 v[10:11], v[174:175], v[138:139], v[10:11] op_sel_hi:[0,1,1]
	v_pk_fma_f32 v[6:7], v[176:177], v[138:139], v[6:7] op_sel_hi:[0,1,1]
	v_pk_fma_f32 v[12:13], v[174:175], v[140:141], v[12:13] op_sel_hi:[0,1,1]
	v_pk_fma_f32 v[8:9], v[176:177], v[140:141], v[8:9] op_sel_hi:[0,1,1]
	global_load_dword v174, v[182:183], off
	global_load_dword v176, v[182:183], off offset:2048
	v_lshl_add_u64 v[182:183], v[182:183], 0, vcc
	s_waitcnt lgkmcnt(7)
	ds_read_b128 v[110:113], v186 offset:256
	ds_read_b128 v[114:117], v186 offset:272
	ds_read_b128 v[118:121], v186 offset:288
	ds_read_b128 v[122:125], v186 offset:304
	ds_read_b128 v[126:129], v186 offset:320
	ds_read_b128 v[130:133], v186 offset:336
	ds_read_b128 v[134:137], v186 offset:352
	ds_read_b128 v[138:141], v186 offset:368
	s_waitcnt vmcnt(2) lgkmcnt(8)
	v_pk_fma_f32 v[68:69], v[178:179], v[142:143], v[68:69] op_sel_hi:[0,1,1]
	v_pk_fma_f32 v[62:63], v[180:181], v[142:143], v[62:63] op_sel_hi:[0,1,1]
	v_pk_fma_f32 v[66:67], v[178:179], v[144:145], v[66:67] op_sel_hi:[0,1,1]
	v_pk_fma_f32 v[64:65], v[180:181], v[144:145], v[64:65] op_sel_hi:[0,1,1]
	v_pk_fma_f32 v[60:61], v[178:179], v[146:147], v[60:61] op_sel_hi:[0,1,1]
	v_pk_fma_f32 v[56:57], v[180:181], v[146:147], v[56:57] op_sel_hi:[0,1,1]
	v_pk_fma_f32 v[58:59], v[178:179], v[148:149], v[58:59] op_sel_hi:[0,1,1]
	v_pk_fma_f32 v[54:55], v[180:181], v[148:149], v[54:55] op_sel_hi:[0,1,1]
	v_pk_fma_f32 v[52:53], v[178:179], v[150:151], v[52:53] op_sel_hi:[0,1,1]
	v_pk_fma_f32 v[48:49], v[180:181], v[150:151], v[48:49] op_sel_hi:[0,1,1]
	v_pk_fma_f32 v[50:51], v[178:179], v[152:153], v[50:51] op_sel_hi:[0,1,1]
	v_pk_fma_f32 v[46:47], v[180:181], v[152:153], v[46:47] op_sel_hi:[0,1,1]
	v_pk_fma_f32 v[44:45], v[178:179], v[154:155], v[44:45] op_sel_hi:[0,1,1]
	v_pk_fma_f32 v[40:41], v[180:181], v[154:155], v[40:41] op_sel_hi:[0,1,1]
	v_pk_fma_f32 v[42:43], v[178:179], v[156:157], v[42:43] op_sel_hi:[0,1,1]
	v_pk_fma_f32 v[38:39], v[180:181], v[156:157], v[38:39] op_sel_hi:[0,1,1]
	v_pk_fma_f32 v[36:37], v[178:179], v[158:159], v[36:37] op_sel_hi:[0,1,1]
	v_pk_fma_f32 v[32:33], v[180:181], v[158:159], v[32:33] op_sel_hi:[0,1,1]
	v_pk_fma_f32 v[34:35], v[178:179], v[160:161], v[34:35] op_sel_hi:[0,1,1]
	v_pk_fma_f32 v[30:31], v[180:181], v[160:161], v[30:31] op_sel_hi:[0,1,1]
	v_pk_fma_f32 v[28:29], v[178:179], v[162:163], v[28:29] op_sel_hi:[0,1,1]
	v_pk_fma_f32 v[24:25], v[180:181], v[162:163], v[24:25] op_sel_hi:[0,1,1]
	v_pk_fma_f32 v[26:27], v[178:179], v[164:165], v[26:27] op_sel_hi:[0,1,1]
	v_pk_fma_f32 v[22:23], v[180:181], v[164:165], v[22:23] op_sel_hi:[0,1,1]
	v_pk_fma_f32 v[20:21], v[178:179], v[166:167], v[20:21] op_sel_hi:[0,1,1]
	v_pk_fma_f32 v[14:15], v[180:181], v[166:167], v[14:15] op_sel_hi:[0,1,1]
	v_pk_fma_f32 v[18:19], v[178:179], v[168:169], v[18:19] op_sel_hi:[0,1,1]
	v_pk_fma_f32 v[16:17], v[180:181], v[168:169], v[16:17] op_sel_hi:[0,1,1]
	v_pk_fma_f32 v[10:11], v[178:179], v[170:171], v[10:11] op_sel_hi:[0,1,1]
	v_pk_fma_f32 v[6:7], v[180:181], v[170:171], v[6:7] op_sel_hi:[0,1,1]
	v_pk_fma_f32 v[12:13], v[178:179], v[172:173], v[12:13] op_sel_hi:[0,1,1]
	v_pk_fma_f32 v[8:9], v[180:181], v[172:173], v[8:9] op_sel_hi:[0,1,1]
	global_load_dword v178, v[182:183], off
	global_load_dword v180, v[182:183], off offset:2048
	v_lshl_add_u64 v[182:183], v[182:183], 0, vcc
	v_add_u32_e32 v186, 0x100, v186
	s_add_i32 s1, s1, -1
	s_cmp_lg_u32 s1, 0
	s_cbranch_scc1 .Lw3_719_loop
; __device__ __forceinline__ void filter_item(const Params& p, int l, int Lf, int t0, float* dst, float* hidT  , int wid0) {
;     ...
; #pragma unroll 16
;     for (int j = 0; j < 64; ++j) {
;         const float wa = w3[j * 1024 + tid], wb = w3[j * 1024 + 512 + tid];
; #pragma unroll
;         for (int g = 0; g < 8; ++g) { const f32x4 hv = *(const f32x4*)(hidT + j * 32 + 4 * g);
; #pragma unroll
;             for (int i = 0; i < 4; ++i) { acc0[4 * g + i] += hv[i] * wa; acc1[4 * g + i] += hv[i] * wb; } }
;     }
;     const float dmin = -3.0701134573253945f, dmax = -15.350567286626973f;
;     const float delta = fabsf(dmin + (float)tid * ((dmax - dmin) / 511.f));
; #pragma unroll
;     for (int g = 0; g < 8; ++g) { f32x4 o0, o1;
; #pragma unroll
;         for (int i = 0; i < 4; ++i) { const float tn = (float)(t0 + 4 * g + i) / (float)(Lf - 1); const float wdw = __expf(-tn * delta); o0[i] = acc0[4 * g + i] * wdw; o1[i] = acc1[4 * g + i] * wdw; }
	s_waitcnt lgkmcnt(7)
	ds_read_b128 v[142:145], v186 offset:128
	ds_read_b128 v[146:149], v186 offset:144
	ds_read_b128 v[150:153], v186 offset:160
	ds_read_b128 v[154:157], v186 offset:176
	ds_read_b128 v[158:161], v186 offset:192
	ds_read_b128 v[162:165], v186 offset:208
	ds_read_b128 v[166:169], v186 offset:224
	ds_read_b128 v[170:173], v186 offset:240
	s_waitcnt vmcnt(2) lgkmcnt(8)
	v_pk_fma_f32 v[68:69], v[174:175], v[110:111], v[68:69] op_sel_hi:[0,1,1]
	v_pk_fma_f32 v[62:63], v[176:177], v[110:111], v[62:63] op_sel_hi:[0,1,1]
	v_pk_fma_f32 v[66:67], v[174:175], v[112:113], v[66:67] op_sel_hi:[0,1,1]
	v_pk_fma_f32 v[64:65], v[176:177], v[112:113], v[64:65] op_sel_hi:[0,1,1]
	v_pk_fma_f32 v[60:61], v[174:175], v[114:115], v[60:61] op_sel_hi:[0,1,1]
	v_pk_fma_f32 v[56:57], v[176:177], v[114:115], v[56:57] op_sel_hi:[0,1,1]
	v_pk_fma_f32 v[58:59], v[174:175], v[116:117], v[58:59] op_sel_hi:[0,1,1]
	v_pk_fma_f32 v[54:55], v[176:177], v[116:117], v[54:55] op_sel_hi:[0,1,1]
	v_pk_fma_f32 v[52:53], v[174:175], v[118:119], v[52:53] op_sel_hi:[0,1,1]
	v_pk_fma_f32 v[48:49], v[176:177], v[118:119], v[48:49] op_sel_hi:[0,1,1]
	v_pk_fma_f32 v[50:51], v[174:175], v[120:121], v[50:51] op_sel_hi:[0,1,1]
	v_pk_fma_f32 v[46:47], v[176:177], v[120:121], v[46:47] op_sel_hi:[0,1,1]
	v_pk_fma_f32 v[44:45], v[174:175], v[122:123], v[44:45] op_sel_hi:[0,1,1]
	v_pk_fma_f32 v[40:41], v[176:177], v[122:123], v[40:41] op_sel_hi:[0,1,1]
	v_pk_fma_f32 v[42:43], v[174:175], v[124:125], v[42:43] op_sel_hi:[0,1,1]
	v_pk_fma_f32 v[38:39], v[176:177], v[124:125], v[38:39] op_sel_hi:[0,1,1]
	v_pk_fma_f32 v[36:37], v[174:175], v[126:127], v[36:37] op_sel_hi:[0,1,1]
	v_pk_fma_f32 v[32:33], v[176:177], v[126:127], v[32:33] op_sel_hi:[0,1,1]
	v_pk_fma_f32 v[34:35], v[174:175], v[128:129], v[34:35] op_sel_hi:[0,1,1]
	v_pk_fma_f32 v[30:31], v[176:177], v[128:129], v[30:31] op_sel_hi:[0,1,1]
	v_pk_fma_f32 v[28:29], v[174:175], v[130:131], v[28:29] op_sel_hi:[0,1,1]
	v_pk_fma_f32 v[24:25], v[176:177], v[130:131], v[24:25] op_sel_hi:[0,1,1]
	v_pk_fma_f32 v[26:27], v[174:175], v[132:133], v[26:27] op_sel_hi:[0,1,1]
	v_pk_fma_f32 v[22:23], v[176:177], v[132:133], v[22:23] op_sel_hi:[0,1,1]
	v_pk_fma_f32 v[20:21], v[174:175], v[134:135], v[20:21] op_sel_hi:[0,1,1]
	v_pk_fma_f32 v[14:15], v[176:177], v[134:135], v[14:15] op_sel_hi:[0,1,1]
	v_pk_fma_f32 v[18:19], v[174:175], v[136:137], v[18:19] op_sel_hi:[0,1,1]
	v_pk_fma_f32 v[16:17], v[176:177], v[136:137], v[16:17] op_sel_hi:[0,1,1]
	v_pk_fma_f32 v[10:11], v[174:175], v[138:139], v[10:11] op_sel_hi:[0,1,1]
	v_pk_fma_f32 v[6:7], v[176:177], v[138:139], v[6:7] op_sel_hi:[0,1,1]
	v_pk_fma_f32 v[12:13], v[174:175], v[140:141], v[12:13] op_sel_hi:[0,1,1]
	v_pk_fma_f32 v[8:9], v[176:177], v[140:141], v[8:9] op_sel_hi:[0,1,1]
	s_waitcnt vmcnt(0) lgkmcnt(0)
	v_pk_fma_f32 v[68:69], v[178:179], v[142:143], v[68:69] op_sel_hi:[0,1,1]
	v_pk_fma_f32 v[62:63], v[180:181], v[142:143], v[62:63] op_sel_hi:[0,1,1]
	v_pk_fma_f32 v[66:67], v[178:179], v[144:145], v[66:67] op_sel_hi:[0,1,1]
	v_pk_fma_f32 v[64:65], v[180:181], v[144:145], v[64:65] op_sel_hi:[0,1,1]
	v_pk_fma_f32 v[60:61], v[178:179], v[146:147], v[60:61] op_sel_hi:[0,1,1]
	v_pk_fma_f32 v[56:57], v[180:181], v[146:147], v[56:57] op_sel_hi:[0,1,1]
	v_pk_fma_f32 v[58:59], v[178:179], v[148:149], v[58:59] op_sel_hi:[0,1,1]
	v_pk_fma_f32 v[54:55], v[180:181], v[148:149], v[54:55] op_sel_hi:[0,1,1]
	v_pk_fma_f32 v[52:53], v[178:179], v[150:151], v[52:53] op_sel_hi:[0,1,1]
	v_pk_fma_f32 v[48:49], v[180:181], v[150:151], v[48:49] op_sel_hi:[0,1,1]
	v_pk_fma_f32 v[50:51], v[178:179], v[152:153], v[50:51] op_sel_hi:[0,1,1]
	v_pk_fma_f32 v[46:47], v[180:181], v[152:153], v[46:47] op_sel_hi:[0,1,1]
	v_pk_fma_f32 v[44:45], v[178:179], v[154:155], v[44:45] op_sel_hi:[0,1,1]
	v_pk_fma_f32 v[40:41], v[180:181], v[154:155], v[40:41] op_sel_hi:[0,1,1]
	v_pk_fma_f32 v[42:43], v[178:179], v[156:157], v[42:43] op_sel_hi:[0,1,1]
	v_pk_fma_f32 v[38:39], v[180:181], v[156:157], v[38:39] op_sel_hi:[0,1,1]
	v_pk_fma_f32 v[36:37], v[178:179], v[158:159], v[36:37] op_sel_hi:[0,1,1]
	v_pk_fma_f32 v[32:33], v[180:181], v[158:159], v[32:33] op_sel_hi:[0,1,1]
	v_pk_fma_f32 v[34:35], v[178:179], v[160:161], v[34:35] op_sel_hi:[0,1,1]
	v_pk_fma_f32 v[30:31], v[180:181], v[160:161], v[30:31] op_sel_hi:[0,1,1]
	v_pk_fma_f32 v[28:29], v[178:179], v[162:163], v[28:29] op_sel_hi:[0,1,1]
	v_pk_fma_f32 v[24:25], v[180:181], v[162:163], v[24:25] op_sel_hi:[0,1,1]
	v_pk_fma_f32 v[26:27], v[178:179], v[164:165], v[26:27] op_sel_hi:[0,1,1]
	v_pk_fma_f32 v[22:23], v[180:181], v[164:165], v[22:23] op_sel_hi:[0,1,1]
	v_pk_fma_f32 v[20:21], v[178:179], v[166:167], v[20:21] op_sel_hi:[0,1,1]
	v_pk_fma_f32 v[14:15], v[180:181], v[166:167], v[14:15] op_sel_hi:[0,1,1]
	v_pk_fma_f32 v[18:19], v[178:179], v[168:169], v[18:19] op_sel_hi:[0,1,1]
	v_pk_fma_f32 v[16:17], v[180:181], v[168:169], v[16:17] op_sel_hi:[0,1,1]
	v_pk_fma_f32 v[10:11], v[178:179], v[170:171], v[10:11] op_sel_hi:[0,1,1]
	v_pk_fma_f32 v[6:7], v[180:181], v[170:171], v[6:7] op_sel_hi:[0,1,1]
	v_pk_fma_f32 v[12:13], v[178:179], v[172:173], v[12:13] op_sel_hi:[0,1,1]
	v_pk_fma_f32 v[8:9], v[180:181], v[172:173], v[8:9] op_sel_hi:[0,1,1]
	s_mov_b32 s0, 0
	v_add_u32_e32 v4, 0x10000, v4
	v_cvt_f32_i32_e32 v5, s74
	s_mov_b32 s6, 0xc5fff800
	v_ashrrev_i32_e32 v3, 31, v2
	v_readlane_b32 s4, v252, 32
	v_div_scale_f32 v70, s[38:39], s6, s6, v5
	v_rcp_f32_e32 v71, v70
	v_cvt_f32_i32_e32 v4, v0
	v_lshlrev_b64 v[0:1], 15, v[0:1]
	v_readlane_b32 s5, v252, 33
	v_fma_f32 v72, -v70, v71, 1.0
	s_ashr_i32 s75, s74, 31
	v_lshlrev_b64 v[2:3], 15, v[2:3]
	v_fmac_f32_e32 v71, v72, v71
; __device__ __forceinline__ void filter_item(const Params& p, int l, int Lf, int t0, float* dst, float* hidT  , int wid0) {
;     ...
;     const float dmin = -3.0701134573253945f, dmax = -15.350567286626973f;
;     const float delta = fabsf(dmin + (float)tid * ((dmax - dmin) / 511.f));
; #pragma unroll
;     for (int g = 0; g < 8; ++g) { f32x4 o0, o1;
; #pragma unroll
;         for (int i = 0; i < 4; ++i) { const float tn = (float)(t0 + 4 * g + i) / (float)(Lf - 1); const float wdw = __expf(-tn * delta); o0[i] = acc0[4 * g + i] * wdw; o1[i] = acc1[4 * g + i] * wdw; }
;         *(f32x4*)(dst + (size_t)tid * Lf + t0 + 4 * g) = o0; *(f32x4*)(dst + (size_t)(512 + tid) * Lf + t0 + 4 * g) = o1; }
	v_div_scale_f32 v72, vcc, v5, s6, v5
	v_lshl_add_u64 v[0:1], s[4:5], 0, v[0:1]
	s_lshl_b64 s[0:1], s[74:75], 2
	v_lshl_add_u64 v[2:3], s[4:5], 0, v[2:3]
	v_mul_f32_e32 v73, v72, v71
	v_lshl_add_u64 v[0:1], v[0:1], 0, s[0:1]
	v_lshl_add_u64 v[2:3], v[2:3], 0, s[0:1]
	v_fma_f32 v74, -v70, v73, v72
	s_or_b32 s0, s74, 1
	v_fmac_f32_e32 v73, v74, v71
	v_cvt_f32_i32_e32 v74, s0
	v_fma_f32 v70, -v70, v73, v72
	v_div_fmas_f32 v70, v70, v71, v73
	v_div_fixup_f32 v5, v70, s6, v5
	v_div_scale_f32 v70, s[0:1], s6, s6, v74
	v_rcp_f32_e32 v71, v70
	v_fmamk_f32 v4, v4, 0xbcc4df2d, v219
	v_mul_f32_e64 v5, v5, |v4|
	v_mul_f32_e32 v5, 0x3fb8aa3b, v5
	v_exp_f32_e32 v72, v5
	v_fma_f32 v5, -v70, v71, 1.0
	v_fmac_f32_e32 v71, v5, v71
	v_div_scale_f32 v5, vcc, v74, s6, v74
	v_mul_f32_e32 v73, v5, v71
	v_fma_f32 v75, -v70, v73, v5
	v_fmac_f32_e32 v73, v75, v71
	s_or_b32 s0, s74, 2
	v_fma_f32 v5, -v70, v73, v5
	v_cvt_f32_i32_e32 v70, s0
	v_div_fmas_f32 v5, v5, v71, v73
	v_div_fixup_f32 v5, v5, s6, v74
	v_mul_f32_e64 v5, v5, |v4|
	v_div_scale_f32 v71, s[0:1], s6, s6, v70
	v_rcp_f32_e32 v74, v71
	v_mul_f32_e32 v5, 0x3fb8aa3b, v5
	v_exp_f32_e32 v73, v5
	s_or_b32 s0, s74, 3
	v_fma_f32 v5, -v71, v74, 1.0
	v_fmac_f32_e32 v74, v5, v74
	v_div_scale_f32 v5, vcc, v70, s6, v70
	v_mul_f32_e32 v75, v5, v74
	v_fma_f32 v76, -v71, v75, v5
	v_fmac_f32_e32 v75, v76, v74
	v_fma_f32 v5, -v71, v75, v5
	v_cvt_f32_i32_e32 v71, s0
	v_div_fmas_f32 v5, v5, v74, v75
	v_div_fixup_f32 v5, v5, s6, v70
	v_mul_f32_e64 v5, v5, |v4|
	v_div_scale_f32 v70, s[0:1], s6, s6, v71
	v_rcp_f32_e32 v75, v70
	v_mul_f32_e32 v5, 0x3fb8aa3b, v5
	v_exp_f32_e32 v74, v5
	s_or_b32 s0, s74, 4
	v_fma_f32 v5, -v70, v75, 1.0
	v_fmac_f32_e32 v75, v5, v75
	v_div_scale_f32 v5, vcc, v71, s6, v71
	v_mul_f32_e32 v76, v5, v75
	v_fma_f32 v77, -v70, v76, v5
	v_fmac_f32_e32 v76, v77, v75
	v_fma_f32 v5, -v70, v76, v5
	v_div_fmas_f32 v5, v5, v75, v76
	v_div_fixup_f32 v5, v5, s6, v71
	v_mul_f32_e64 v5, v5, |v4|
	v_mul_f32_e32 v5, 0x3fb8aa3b, v5
	v_exp_f32_e32 v75, v5
	v_cvt_f32_i32_e32 v5, s0
	v_pk_mul_f32 v[68:69], v[72:73], v[68:69]
	v_pk_mul_f32 v[62:63], v[72:73], v[62:63]
	v_pk_mul_f32 v[70:71], v[74:75], v[66:67]
	v_div_scale_f32 v66, s[0:1], s6, s6, v5
	v_rcp_f32_e32 v67, v66
	v_pk_mul_f32 v[64:65], v[74:75], v[64:65]
	global_store_dwordx4 v[0:1], v[68:71], off
	global_store_dwordx4 v[2:3], v[62:65], off
	s_or_b32 s0, s74, 5
	s_add_i32 s26, s26, s24
	v_fma_f32 v62, -v66, v67, 1.0
	v_fmac_f32_e32 v67, v62, v67
	v_div_scale_f32 v62, vcc, v5, s6, v5
	v_mul_f32_e32 v63, v62, v67
	v_fma_f32 v64, -v66, v63, v62
	v_cvt_f32_i32_e32 v65, s0
	v_fmac_f32_e32 v63, v64, v67
	v_fma_f32 v62, -v66, v63, v62
	v_div_fmas_f32 v62, v62, v67, v63
	v_div_fixup_f32 v5, v62, s6, v5
	v_div_scale_f32 v62, s[0:1], s6, s6, v65
	v_rcp_f32_e32 v63, v62
	v_mul_f32_e64 v5, v5, |v4|
	v_mul_f32_e32 v5, 0x3fb8aa3b, v5
	v_exp_f32_e32 v64, v5
	v_fma_f32 v5, -v62, v63, 1.0
	v_fmac_f32_e32 v63, v5, v63
	v_div_scale_f32 v5, vcc, v65, s6, v65
	v_mul_f32_e32 v66, v5, v63
	v_fma_f32 v67, -v62, v66, v5
	v_fmac_f32_e32 v66, v67, v63
	s_or_b32 s0, s74, 6
	v_fma_f32 v5, -v62, v66, v5
	v_cvt_f32_i32_e32 v62, s0
	v_div_fmas_f32 v5, v5, v63, v66
	v_div_fixup_f32 v5, v5, s6, v65
	v_mul_f32_e64 v5, v5, |v4|
	v_div_scale_f32 v63, s[0:1], s6, s6, v62
	v_rcp_f32_e32 v66, v63
	v_mul_f32_e32 v5, 0x3fb8aa3b, v5
	v_exp_f32_e32 v65, v5
	s_or_b32 s0, s74, 7
	v_fma_f32 v5, -v63, v66, 1.0
	v_fmac_f32_e32 v66, v5, v66
	v_div_scale_f32 v5, vcc, v62, s6, v62
	v_mul_f32_e32 v67, v5, v66
	v_fma_f32 v68, -v63, v67, v5
	v_fmac_f32_e32 v67, v68, v66
	v_fma_f32 v5, -v63, v67, v5
	v_cvt_f32_i32_e32 v63, s0
	v_div_fmas_f32 v5, v5, v66, v67
	v_div_fixup_f32 v5, v5, s6, v62
	v_mul_f32_e64 v5, v5, |v4|
	v_div_scale_f32 v62, s[0:1], s6, s6, v63
	v_rcp_f32_e32 v67, v62
	v_mul_f32_e32 v5, 0x3fb8aa3b, v5
	v_exp_f32_e32 v66, v5
	s_or_b32 s0, s74, 8
	v_fma_f32 v5, -v62, v67, 1.0
	v_fmac_f32_e32 v67, v5, v67
	v_div_scale_f32 v5, vcc, v63, s6, v63
	v_mul_f32_e32 v68, v5, v67
	v_fma_f32 v69, -v62, v68, v5
	v_fmac_f32_e32 v68, v69, v67
	v_fma_f32 v5, -v62, v68, v5
	v_div_fmas_f32 v5, v5, v67, v68
	v_div_fixup_f32 v5, v5, s6, v63
	v_mul_f32_e64 v5, v5, |v4|
	v_mul_f32_e32 v5, 0x3fb8aa3b, v5
	v_exp_f32_e32 v67, v5
	v_cvt_f32_i32_e32 v5, s0
	v_pk_mul_f32 v[60:61], v[64:65], v[60:61]
	v_pk_mul_f32 v[56:57], v[64:65], v[56:57]
	v_pk_mul_f32 v[62:63], v[66:67], v[58:59]
	v_div_scale_f32 v64, s[0:1], s6, s6, v5
	v_rcp_f32_e32 v65, v64
	v_pk_mul_f32 v[58:59], v[66:67], v[54:55]
	s_or_b32 s0, s74, 9
	global_store_dwordx4 v[0:1], v[60:63], off offset:16
	global_store_dwordx4 v[2:3], v[56:59], off offset:16
	v_fma_f32 v54, -v64, v65, 1.0
	v_fmac_f32_e32 v65, v54, v65
	v_div_scale_f32 v54, vcc, v5, s6, v5
	v_mul_f32_e32 v55, v54, v65
	v_fma_f32 v56, -v64, v55, v54
	v_cvt_f32_i32_e32 v57, s0
	v_fmac_f32_e32 v55, v56, v65
	v_fma_f32 v54, -v64, v55, v54
	v_div_fmas_f32 v54, v54, v65, v55
	v_div_fixup_f32 v5, v54, s6, v5
	v_div_scale_f32 v54, s[0:1], s6, s6, v57
	v_rcp_f32_e32 v55, v54
	v_mul_f32_e64 v5, v5, |v4|
	v_mul_f32_e32 v5, 0x3fb8aa3b, v5
	v_exp_f32_e32 v56, v5
	v_fma_f32 v5, -v54, v55, 1.0
	v_fmac_f32_e32 v55, v5, v55
	v_div_scale_f32 v5, vcc, v57, s6, v57
	v_mul_f32_e32 v58, v5, v55
	v_fma_f32 v59, -v54, v58, v5
	v_fmac_f32_e32 v58, v59, v55
	s_or_b32 s0, s74, 10
	v_fma_f32 v5, -v54, v58, v5
	v_cvt_f32_i32_e32 v54, s0
	v_div_fmas_f32 v5, v5, v55, v58
	v_div_fixup_f32 v5, v5, s6, v57
	v_mul_f32_e64 v5, v5, |v4|
	v_div_scale_f32 v55, s[0:1], s6, s6, v54
	v_rcp_f32_e32 v58, v55
	v_mul_f32_e32 v5, 0x3fb8aa3b, v5
	v_exp_f32_e32 v57, v5
	s_or_b32 s0, s74, 11
	v_fma_f32 v5, -v55, v58, 1.0
	v_fmac_f32_e32 v58, v5, v58
; __device__ __forceinline__ void filter_item(const Params& p, int l, int Lf, int t0, float* dst, float* hidT  , int wid0) {
;     ...
;     const float dmin = -3.0701134573253945f, dmax = -15.350567286626973f;
;     const float delta = fabsf(dmin + (float)tid * ((dmax - dmin) / 511.f));
; #pragma unroll
;     for (int g = 0; g < 8; ++g) { f32x4 o0, o1;
; #pragma unroll
;         for (int i = 0; i < 4; ++i) { const float tn = (float)(t0 + 4 * g + i) / (float)(Lf - 1); const float wdw = __expf(-tn * delta); o0[i] = acc0[4 * g + i] * wdw; o1[i] = acc1[4 * g + i] * wdw; }
;         *(f32x4*)(dst + (size_t)tid * Lf + t0 + 4 * g) = o0; *(f32x4*)(dst + (size_t)(512 + tid) * Lf + t0 + 4 * g) = o1; }
	v_div_scale_f32 v5, vcc, v54, s6, v54
	v_mul_f32_e32 v59, v5, v58
	v_fma_f32 v60, -v55, v59, v5
	v_fmac_f32_e32 v59, v60, v58
	v_fma_f32 v5, -v55, v59, v5
	v_cvt_f32_i32_e32 v55, s0
	v_div_fmas_f32 v5, v5, v58, v59
	v_div_fixup_f32 v5, v5, s6, v54
	v_mul_f32_e64 v5, v5, |v4|
	v_div_scale_f32 v54, s[0:1], s6, s6, v55
	v_rcp_f32_e32 v59, v54
	v_mul_f32_e32 v5, 0x3fb8aa3b, v5
	v_exp_f32_e32 v58, v5
	s_or_b32 s0, s74, 12
	v_fma_f32 v5, -v54, v59, 1.0
	v_fmac_f32_e32 v59, v5, v59
	v_div_scale_f32 v5, vcc, v55, s6, v55
	v_mul_f32_e32 v60, v5, v59
	v_fma_f32 v61, -v54, v60, v5
	v_fmac_f32_e32 v60, v61, v59
	v_fma_f32 v5, -v54, v60, v5
	v_div_fmas_f32 v5, v5, v59, v60
	v_div_fixup_f32 v5, v5, s6, v55
	v_mul_f32_e64 v5, v5, |v4|
	v_mul_f32_e32 v5, 0x3fb8aa3b, v5
	v_exp_f32_e32 v59, v5
	v_cvt_f32_i32_e32 v5, s0
	v_pk_mul_f32 v[52:53], v[56:57], v[52:53]
	v_pk_mul_f32 v[48:49], v[56:57], v[48:49]
	v_pk_mul_f32 v[54:55], v[58:59], v[50:51]
	v_div_scale_f32 v56, s[0:1], s6, s6, v5
	v_rcp_f32_e32 v57, v56
	v_pk_mul_f32 v[50:51], v[58:59], v[46:47]
	s_or_b32 s0, s74, 13
	global_store_dwordx4 v[0:1], v[52:55], off offset:32
	global_store_dwordx4 v[2:3], v[48:51], off offset:32
	v_fma_f32 v46, -v56, v57, 1.0
	v_fmac_f32_e32 v57, v46, v57
	v_div_scale_f32 v46, vcc, v5, s6, v5
	v_mul_f32_e32 v47, v46, v57
	v_fma_f32 v48, -v56, v47, v46
	v_cvt_f32_i32_e32 v49, s0
	v_fmac_f32_e32 v47, v48, v57
	v_fma_f32 v46, -v56, v47, v46
	v_div_fmas_f32 v46, v46, v57, v47
	v_div_fixup_f32 v5, v46, s6, v5
	v_div_scale_f32 v46, s[0:1], s6, s6, v49
	v_rcp_f32_e32 v47, v46
	v_mul_f32_e64 v5, v5, |v4|
	v_mul_f32_e32 v5, 0x3fb8aa3b, v5
	v_exp_f32_e32 v48, v5
	v_fma_f32 v5, -v46, v47, 1.0
	v_fmac_f32_e32 v47, v5, v47
	v_div_scale_f32 v5, vcc, v49, s6, v49
	v_mul_f32_e32 v50, v5, v47
	v_fma_f32 v51, -v46, v50, v5
	v_fmac_f32_e32 v50, v51, v47
	s_or_b32 s0, s74, 14
	v_fma_f32 v5, -v46, v50, v5
	v_cvt_f32_i32_e32 v46, s0
	v_div_fmas_f32 v5, v5, v47, v50
	v_div_fixup_f32 v5, v5, s6, v49
	v_mul_f32_e64 v5, v5, |v4|
	v_div_scale_f32 v47, s[0:1], s6, s6, v46
	v_rcp_f32_e32 v50, v47
	v_mul_f32_e32 v5, 0x3fb8aa3b, v5
	v_exp_f32_e32 v49, v5
	s_or_b32 s0, s74, 15
	v_fma_f32 v5, -v47, v50, 1.0
	v_fmac_f32_e32 v50, v5, v50
	v_div_scale_f32 v5, vcc, v46, s6, v46
	v_mul_f32_e32 v51, v5, v50
	v_fma_f32 v52, -v47, v51, v5
	v_fmac_f32_e32 v51, v52, v50
	v_fma_f32 v5, -v47, v51, v5
	v_cvt_f32_i32_e32 v47, s0
	v_div_fmas_f32 v5, v5, v50, v51
	v_div_fixup_f32 v5, v5, s6, v46
	v_mul_f32_e64 v5, v5, |v4|
	v_div_scale_f32 v46, s[0:1], s6, s6, v47
	v_rcp_f32_e32 v51, v46
	v_mul_f32_e32 v5, 0x3fb8aa3b, v5
	v_exp_f32_e32 v50, v5
	s_or_b32 s0, s74, 16
	v_fma_f32 v5, -v46, v51, 1.0
	v_fmac_f32_e32 v51, v5, v51
	v_div_scale_f32 v5, vcc, v47, s6, v47
	v_mul_f32_e32 v52, v5, v51
	v_fma_f32 v53, -v46, v52, v5
	v_fmac_f32_e32 v52, v53, v51
	v_fma_f32 v5, -v46, v52, v5
	v_div_fmas_f32 v5, v5, v51, v52
	v_div_fixup_f32 v5, v5, s6, v47
	v_mul_f32_e64 v5, v5, |v4|
	v_mul_f32_e32 v5, 0x3fb8aa3b, v5
	v_exp_f32_e32 v51, v5
	v_cvt_f32_i32_e32 v5, s0
	v_pk_mul_f32 v[44:45], v[48:49], v[44:45]
	v_pk_mul_f32 v[40:41], v[48:49], v[40:41]
	v_pk_mul_f32 v[46:47], v[50:51], v[42:43]
	v_div_scale_f32 v48, s[0:1], s6, s6, v5
	v_rcp_f32_e32 v49, v48
	v_pk_mul_f32 v[42:43], v[50:51], v[38:39]
	s_or_b32 s0, s74, 17
	global_store_dwordx4 v[0:1], v[44:47], off offset:48
	global_store_dwordx4 v[2:3], v[40:43], off offset:48
	v_fma_f32 v38, -v48, v49, 1.0
	v_fmac_f32_e32 v49, v38, v49
	v_div_scale_f32 v38, vcc, v5, s6, v5
	v_mul_f32_e32 v39, v38, v49
	v_fma_f32 v40, -v48, v39, v38
	v_cvt_f32_i32_e32 v41, s0
	v_fmac_f32_e32 v39, v40, v49
	v_fma_f32 v38, -v48, v39, v38
	v_div_fmas_f32 v38, v38, v49, v39
	v_div_fixup_f32 v5, v38, s6, v5
	v_div_scale_f32 v38, s[0:1], s6, s6, v41
	v_rcp_f32_e32 v39, v38
	v_mul_f32_e64 v5, v5, |v4|
	v_mul_f32_e32 v5, 0x3fb8aa3b, v5
	v_exp_f32_e32 v40, v5
	v_fma_f32 v5, -v38, v39, 1.0
	v_fmac_f32_e32 v39, v5, v39
	v_div_scale_f32 v5, vcc, v41, s6, v41
	v_mul_f32_e32 v42, v5, v39
	v_fma_f32 v43, -v38, v42, v5
	v_fmac_f32_e32 v42, v43, v39
	s_or_b32 s0, s74, 18
	v_fma_f32 v5, -v38, v42, v5
	v_cvt_f32_i32_e32 v38, s0
	v_div_fmas_f32 v5, v5, v39, v42
	v_div_fixup_f32 v5, v5, s6, v41
	v_mul_f32_e64 v5, v5, |v4|
	v_div_scale_f32 v39, s[0:1], s6, s6, v38
	v_rcp_f32_e32 v42, v39
	v_mul_f32_e32 v5, 0x3fb8aa3b, v5
	v_exp_f32_e32 v41, v5
	s_or_b32 s0, s74, 19
	v_fma_f32 v5, -v39, v42, 1.0
	v_fmac_f32_e32 v42, v5, v42
	v_div_scale_f32 v5, vcc, v38, s6, v38
	v_mul_f32_e32 v43, v5, v42
	v_fma_f32 v44, -v39, v43, v5
	v_fmac_f32_e32 v43, v44, v42
	v_fma_f32 v5, -v39, v43, v5
	v_cvt_f32_i32_e32 v39, s0
	v_div_fmas_f32 v5, v5, v42, v43
	v_div_fixup_f32 v5, v5, s6, v38
	v_mul_f32_e64 v5, v5, |v4|
	v_div_scale_f32 v38, s[0:1], s6, s6, v39
	v_rcp_f32_e32 v43, v38
	v_mul_f32_e32 v5, 0x3fb8aa3b, v5
	v_exp_f32_e32 v42, v5
	s_or_b32 s0, s74, 20
	v_fma_f32 v5, -v38, v43, 1.0
	v_fmac_f32_e32 v43, v5, v43
	v_div_scale_f32 v5, vcc, v39, s6, v39
	v_mul_f32_e32 v44, v5, v43
	v_fma_f32 v45, -v38, v44, v5
	v_fmac_f32_e32 v44, v45, v43
	v_fma_f32 v5, -v38, v44, v5
	v_div_fmas_f32 v5, v5, v43, v44
	v_div_fixup_f32 v5, v5, s6, v39
	v_mul_f32_e64 v5, v5, |v4|
	v_mul_f32_e32 v5, 0x3fb8aa3b, v5
	v_exp_f32_e32 v43, v5
	v_cvt_f32_i32_e32 v5, s0
	v_pk_mul_f32 v[36:37], v[40:41], v[36:37]
	v_pk_mul_f32 v[32:33], v[40:41], v[32:33]
	v_pk_mul_f32 v[38:39], v[42:43], v[34:35]
	v_div_scale_f32 v40, s[0:1], s6, s6, v5
	v_rcp_f32_e32 v41, v40
	v_pk_mul_f32 v[34:35], v[42:43], v[30:31]
	s_or_b32 s0, s74, 21
	global_store_dwordx4 v[0:1], v[36:39], off offset:64
	global_store_dwordx4 v[2:3], v[32:35], off offset:64
	v_fma_f32 v30, -v40, v41, 1.0
; __device__ __forceinline__ void filter_item(const Params& p, int l, int Lf, int t0, float* dst, float* hidT  , int wid0) {
;     ...
;     const float dmin = -3.0701134573253945f, dmax = -15.350567286626973f;
;     const float delta = fabsf(dmin + (float)tid * ((dmax - dmin) / 511.f));
; #pragma unroll
;     for (int g = 0; g < 8; ++g) { f32x4 o0, o1;
; #pragma unroll
;         for (int i = 0; i < 4; ++i) { const float tn = (float)(t0 + 4 * g + i) / (float)(Lf - 1); const float wdw = __expf(-tn * delta); o0[i] = acc0[4 * g + i] * wdw; o1[i] = acc1[4 * g + i] * wdw; }
;         *(f32x4*)(dst + (size_t)tid * Lf + t0 + 4 * g) = o0; *(f32x4*)(dst + (size_t)(512 + tid) * Lf + t0 + 4 * g) = o1; }
;     __syncthreads();
; __device__ __forceinline__ void phaseA(const Params& p, int l, unsigned char* lds, int wid0) {
;     ...
;     { float* hidT = (float*)(lds + 104448);
;       for (int it = blockIdx.x; it < 256; it += gridDim.x) filter_item(p, l, SEQ, 32 * it, (float*)(ws + WS_FILT), hidT, wid0);
;       }
	v_fmac_f32_e32 v41, v30, v41
	v_div_scale_f32 v30, vcc, v5, s6, v5
	v_mul_f32_e32 v31, v30, v41
	v_fma_f32 v32, -v40, v31, v30
	v_cvt_f32_i32_e32 v33, s0
	v_fmac_f32_e32 v31, v32, v41
	v_fma_f32 v30, -v40, v31, v30
	v_div_fmas_f32 v30, v30, v41, v31
	v_div_fixup_f32 v5, v30, s6, v5
	v_div_scale_f32 v30, s[0:1], s6, s6, v33
	v_rcp_f32_e32 v31, v30
	v_mul_f32_e64 v5, v5, |v4|
	v_mul_f32_e32 v5, 0x3fb8aa3b, v5
	v_exp_f32_e32 v32, v5
	v_fma_f32 v5, -v30, v31, 1.0
	v_fmac_f32_e32 v31, v5, v31
	v_div_scale_f32 v5, vcc, v33, s6, v33
	v_mul_f32_e32 v34, v5, v31
	v_fma_f32 v35, -v30, v34, v5
	v_fmac_f32_e32 v34, v35, v31
	s_or_b32 s0, s74, 22
	v_fma_f32 v5, -v30, v34, v5
	v_cvt_f32_i32_e32 v30, s0
	v_div_fmas_f32 v5, v5, v31, v34
	v_div_fixup_f32 v5, v5, s6, v33
	v_mul_f32_e64 v5, v5, |v4|
	v_div_scale_f32 v31, s[0:1], s6, s6, v30
	v_rcp_f32_e32 v34, v31
	v_mul_f32_e32 v5, 0x3fb8aa3b, v5
	v_exp_f32_e32 v33, v5
	s_or_b32 s0, s74, 23
	v_fma_f32 v5, -v31, v34, 1.0
	v_fmac_f32_e32 v34, v5, v34
	v_div_scale_f32 v5, vcc, v30, s6, v30
	v_mul_f32_e32 v35, v5, v34
	v_fma_f32 v36, -v31, v35, v5
	v_fmac_f32_e32 v35, v36, v34
	v_fma_f32 v5, -v31, v35, v5
	v_cvt_f32_i32_e32 v31, s0
	v_div_fmas_f32 v5, v5, v34, v35
	v_div_fixup_f32 v5, v5, s6, v30
	v_mul_f32_e64 v5, v5, |v4|
	v_div_scale_f32 v30, s[0:1], s6, s6, v31
	v_rcp_f32_e32 v35, v30
	v_mul_f32_e32 v5, 0x3fb8aa3b, v5
	v_exp_f32_e32 v34, v5
	s_or_b32 s0, s74, 24
	v_fma_f32 v5, -v30, v35, 1.0
	v_fmac_f32_e32 v35, v5, v35
	v_div_scale_f32 v5, vcc, v31, s6, v31
	v_mul_f32_e32 v36, v5, v35
	v_fma_f32 v37, -v30, v36, v5
	v_fmac_f32_e32 v36, v37, v35
	v_fma_f32 v5, -v30, v36, v5
	v_div_fmas_f32 v5, v5, v35, v36
	v_div_fixup_f32 v5, v5, s6, v31
	v_mul_f32_e64 v5, v5, |v4|
	v_mul_f32_e32 v5, 0x3fb8aa3b, v5
	v_exp_f32_e32 v35, v5
	v_cvt_f32_i32_e32 v5, s0
	v_pk_mul_f32 v[28:29], v[32:33], v[28:29]
	v_pk_mul_f32 v[24:25], v[32:33], v[24:25]
	v_pk_mul_f32 v[30:31], v[34:35], v[26:27]
	v_div_scale_f32 v32, s[0:1], s6, s6, v5
	v_rcp_f32_e32 v33, v32
	v_pk_mul_f32 v[26:27], v[34:35], v[22:23]
	s_or_b32 s0, s74, 25
	global_store_dwordx4 v[0:1], v[28:31], off offset:80
	global_store_dwordx4 v[2:3], v[24:27], off offset:80
	v_fma_f32 v22, -v32, v33, 1.0
	v_fmac_f32_e32 v33, v22, v33
	v_div_scale_f32 v22, vcc, v5, s6, v5
	v_mul_f32_e32 v23, v22, v33
	v_fma_f32 v24, -v32, v23, v22
	v_cvt_f32_i32_e32 v25, s0
	v_fmac_f32_e32 v23, v24, v33
	v_fma_f32 v22, -v32, v23, v22
	v_div_fmas_f32 v22, v22, v33, v23
	v_div_fixup_f32 v5, v22, s6, v5
	v_div_scale_f32 v22, s[0:1], s6, s6, v25
	v_rcp_f32_e32 v23, v22
	v_mul_f32_e64 v5, v5, |v4|
	v_mul_f32_e32 v5, 0x3fb8aa3b, v5
	v_exp_f32_e32 v24, v5
	v_fma_f32 v5, -v22, v23, 1.0
	v_fmac_f32_e32 v23, v5, v23
	v_div_scale_f32 v5, vcc, v25, s6, v25
	v_mul_f32_e32 v26, v5, v23
	v_fma_f32 v27, -v22, v26, v5
	v_fmac_f32_e32 v26, v27, v23
	s_or_b32 s0, s74, 26
	v_fma_f32 v5, -v22, v26, v5
	v_cvt_f32_i32_e32 v22, s0
	v_div_fmas_f32 v5, v5, v23, v26
	v_div_fixup_f32 v5, v5, s6, v25
	v_mul_f32_e64 v5, v5, |v4|
	v_div_scale_f32 v23, s[0:1], s6, s6, v22
	v_rcp_f32_e32 v26, v23
	v_mul_f32_e32 v5, 0x3fb8aa3b, v5
	v_exp_f32_e32 v25, v5
	s_or_b32 s0, s74, 27
	v_fma_f32 v5, -v23, v26, 1.0
	v_fmac_f32_e32 v26, v5, v26
	v_div_scale_f32 v5, vcc, v22, s6, v22
	v_mul_f32_e32 v27, v5, v26
	v_fma_f32 v28, -v23, v27, v5
	v_fmac_f32_e32 v27, v28, v26
	v_fma_f32 v5, -v23, v27, v5
	v_cvt_f32_i32_e32 v23, s0
	v_div_fmas_f32 v5, v5, v26, v27
	v_div_fixup_f32 v5, v5, s6, v22
	v_mul_f32_e64 v5, v5, |v4|
	v_div_scale_f32 v22, s[0:1], s6, s6, v23
	v_rcp_f32_e32 v27, v22
	v_mul_f32_e32 v5, 0x3fb8aa3b, v5
	v_exp_f32_e32 v26, v5
	s_or_b32 s0, s74, 28
	v_fma_f32 v5, -v22, v27, 1.0
	v_fmac_f32_e32 v27, v5, v27
	v_div_scale_f32 v5, vcc, v23, s6, v23
	v_mul_f32_e32 v28, v5, v27
	v_fma_f32 v29, -v22, v28, v5
	v_fmac_f32_e32 v28, v29, v27
	v_fma_f32 v5, -v22, v28, v5
	v_div_fmas_f32 v5, v5, v27, v28
	v_cvt_f32_i32_e32 v28, s0
	v_div_fixup_f32 v5, v5, s6, v23
	v_mul_f32_e64 v5, v5, |v4|
	v_mul_f32_e32 v5, 0x3fb8aa3b, v5
	v_exp_f32_e32 v27, v5
	v_div_scale_f32 v5, s[0:1], s6, s6, v28
	v_rcp_f32_e32 v29, v5
	v_pk_mul_f32 v[22:23], v[26:27], v[18:19]
	v_pk_mul_f32 v[20:21], v[24:25], v[20:21]
	v_pk_mul_f32 v[14:15], v[24:25], v[14:15]
	v_fma_f32 v18, -v5, v29, 1.0
	v_fmac_f32_e32 v29, v18, v29
	v_div_scale_f32 v18, vcc, v28, s6, v28
	v_mul_f32_e32 v19, v18, v29
	v_fma_f32 v24, -v5, v19, v18
	s_or_b32 s0, s74, 29
	v_fmac_f32_e32 v19, v24, v29
	v_cvt_f32_i32_e32 v24, s0
	v_fma_f32 v5, -v5, v19, v18
	v_div_fmas_f32 v5, v5, v29, v19
	v_div_fixup_f32 v5, v5, s6, v28
	v_div_scale_f32 v19, s[0:1], s6, s6, v24
	v_rcp_f32_e32 v25, v19
	v_mul_f32_e64 v5, v5, |v4|
	v_mul_f32_e32 v5, 0x3fb8aa3b, v5
	v_exp_f32_e32 v18, v5
	v_fma_f32 v5, -v19, v25, 1.0
	v_fmac_f32_e32 v25, v5, v25
	v_div_scale_f32 v5, vcc, v24, s6, v24
	v_pk_mul_f32 v[16:17], v[26:27], v[16:17]
	v_mul_f32_e32 v26, v5, v25
	v_fma_f32 v27, -v19, v26, v5
	s_or_b32 s0, s74, 30
	v_fmac_f32_e32 v26, v27, v25
	v_cvt_f32_i32_e32 v27, s0
	v_fma_f32 v5, -v19, v26, v5
	v_div_fmas_f32 v5, v5, v25, v26
	v_div_fixup_f32 v5, v5, s6, v24
	v_div_scale_f32 v24, s[0:1], s6, s6, v27
	v_rcp_f32_e32 v25, v24
	v_mul_f32_e64 v5, v5, |v4|
	v_mul_f32_e32 v5, 0x3fb8aa3b, v5
	v_exp_f32_e32 v19, v5
	v_fma_f32 v5, -v24, v25, 1.0
	v_fmac_f32_e32 v25, v5, v25
	v_div_scale_f32 v5, vcc, v27, s6, v27
	v_mul_f32_e32 v26, v5, v25
	v_fma_f32 v28, -v24, v26, v5
	s_or_b32 s0, s74, 31
	v_fmac_f32_e32 v26, v28, v25
	v_cvt_f32_i32_e32 v28, s0
	v_fma_f32 v5, -v24, v26, v5
	v_div_fmas_f32 v5, v5, v25, v26
	v_div_fixup_f32 v5, v5, s6, v27
	v_div_scale_f32 v25, s[0:1], s6, s6, v28
	v_rcp_f32_e32 v26, v25
	v_mul_f32_e64 v5, v5, |v4|
	v_mul_f32_e32 v5, 0x3fb8aa3b, v5
	v_exp_f32_e32 v24, v5
	v_fma_f32 v5, -v25, v26, 1.0
	v_fmac_f32_e32 v26, v5, v26
	v_div_scale_f32 v5, vcc, v28, s6, v28
	v_mul_f32_e32 v27, v5, v26
	v_fma_f32 v29, -v25, v27, v5
	v_fmac_f32_e32 v27, v29, v26
	v_fma_f32 v5, -v25, v27, v5
	v_div_fmas_f32 v5, v5, v26, v27
	v_div_fixup_f32 v5, v5, s6, v28
	v_mul_f32_e64 v4, v5, |v4|
	v_mul_f32_e32 v4, 0x3fb8aa3b, v4
	v_exp_f32_e32 v25, v4
	v_pk_mul_f32 v[10:11], v[18:19], v[10:11]
	s_cmpk_gt_i32 s26, 0xff
	s_mov_b32 s75, 0x18000
	v_pk_mul_f32 v[12:13], v[24:25], v[12:13]
	global_store_dwordx4 v[0:1], v[20:23], off offset:96
	global_store_dwordx4 v[2:3], v[14:17], off offset:96
	v_pk_mul_f32 v[4:5], v[18:19], v[6:7]
	v_pk_mul_f32 v[6:7], v[24:25], v[8:9]
	global_store_dwordx4 v[0:1], v[10:13], off offset:112
	global_store_dwordx4 v[2:3], v[4:7], off offset:112
	s_barrier
	s_cbranch_scc0 .LBB0_592
	s_branch .LBB0_725
